# readout per-token loop hand-scheduled (pipelined LDS reads, packed FMAs, prefetched loads)
# speedup vs baseline: 1.1075x; 1.0182x over previous
.LBB0_1128:
	s_or_b64 exec, exec, s[2:3]
	v_ashrrev_i32_e32 v49, 31, v48
	v_lshlrev_b64 v[54:55], 2, v[48:49]
	v_lshl_add_u64 v[42:43], s[0:1], 0, v[54:55]
	v_mov_b32_e32 v96, v54
	global_load_dword v2, v96, s[0:1]
	global_load_dword v3, v96, s[0:1] offset:1024
	global_load_dword v4, v96, s[0:1] offset:2048
	global_load_dword v5, v96, s[0:1] offset:3072
	v_add_u32_e32 v96, 0x1000, v96
	global_load_dword v6, v96, s[0:1]
	global_load_dword v7, v96, s[0:1] offset:1024
	global_load_dword v8, v96, s[0:1] offset:2048
	global_load_dword v9, v96, s[0:1] offset:3072
	v_add_u32_e32 v96, 0x1000, v96
	global_load_dword v10, v96, s[0:1]
	global_load_dword v11, v96, s[0:1] offset:1024
	global_load_dword v12, v96, s[0:1] offset:2048
	global_load_dword v13, v96, s[0:1] offset:3072
	v_add_u32_e32 v96, 0x1000, v96
	global_load_dword v14, v96, s[0:1]
	global_load_dword v15, v96, s[0:1] offset:1024
	global_load_dword v16, v96, s[0:1] offset:2048
	global_load_dword v17, v96, s[0:1] offset:3072
	v_add_u32_e32 v96, 0x1000, v96
	global_load_dword v18, v96, s[0:1]
	global_load_dword v19, v96, s[0:1] offset:1024
	global_load_dword v20, v96, s[0:1] offset:2048
	global_load_dword v21, v96, s[0:1] offset:3072
	v_add_u32_e32 v96, 0x1000, v96
	global_load_dword v22, v96, s[0:1]
	global_load_dword v23, v96, s[0:1] offset:1024
	global_load_dword v24, v96, s[0:1] offset:2048
	global_load_dword v25, v96, s[0:1] offset:3072
	v_add_u32_e32 v96, 0x1000, v96
	global_load_dword v26, v96, s[0:1]
	global_load_dword v27, v96, s[0:1] offset:1024
	global_load_dword v28, v96, s[0:1] offset:2048
	global_load_dword v29, v96, s[0:1] offset:3072
	v_add_u32_e32 v96, 0x1000, v96
	global_load_dword v30, v96, s[0:1]
	global_load_dword v31, v96, s[0:1] offset:1024
	global_load_dword v32, v96, s[0:1] offset:2048
	global_load_dword v33, v96, s[0:1] offset:3072
	v_add_u32_e32 v96, 0x1000, v96
	global_load_dword v34, v96, s[0:1]
	global_load_dword v35, v96, s[0:1] offset:1024
	global_load_dword v36, v96, s[0:1] offset:2048
	global_load_dword v37, v96, s[0:1] offset:3072
	v_add_u32_e32 v96, 0x1000, v96
	global_load_dword v38, v96, s[0:1]
	global_load_dword v39, v96, s[0:1] offset:1024
	global_load_dword v40, v96, s[0:1] offset:2048
	global_load_dword v41, v96, s[0:1] offset:3072
	v_add_u32_e32 v96, 0x1000, v96
	global_load_dword v58, v96, s[0:1]
	global_load_dword v59, v96, s[0:1] offset:1024
	global_load_dword v60, v96, s[0:1] offset:2048
	global_load_dword v61, v96, s[0:1] offset:3072
	v_add_u32_e32 v96, 0x1000, v96
	global_load_dword v62, v96, s[0:1]
	global_load_dword v63, v96, s[0:1] offset:1024
	global_load_dword v64, v96, s[0:1] offset:2048
	global_load_dword v65, v96, s[0:1] offset:3072
	v_add_u32_e32 v96, 0x1000, v96
	global_load_dword v66, v96, s[0:1]
	global_load_dword v67, v96, s[0:1] offset:1024
	global_load_dword v68, v96, s[0:1] offset:2048
	global_load_dword v69, v96, s[0:1] offset:3072
	v_add_u32_e32 v96, 0x1000, v96
	global_load_dword v70, v96, s[0:1]
	global_load_dword v71, v96, s[0:1] offset:1024
	global_load_dword v72, v96, s[0:1] offset:2048
	global_load_dword v73, v96, s[0:1] offset:3072
	v_add_u32_e32 v96, 0x1000, v96
	global_load_dword v74, v96, s[0:1]
	global_load_dword v75, v96, s[0:1] offset:1024
	global_load_dword v76, v96, s[0:1] offset:2048
	global_load_dword v77, v96, s[0:1] offset:3072
	v_add_u32_e32 v96, 0x1000, v96
	global_load_dword v78, v96, s[0:1]
	global_load_dword v79, v96, s[0:1] offset:1024
	global_load_dword v80, v96, s[0:1] offset:2048
	global_load_dword v81, v96, s[0:1] offset:3072
	s_movk_i32 s2, 0x1000
	s_movk_i32 s3, 0x2000
	s_movk_i32 s2, 0x3000
	s_nop 0
	s_mov_b32 s4, 0xb000
	s_nop 0
	s_movk_i32 s2, 0x5000
	s_nop 0
	v_readlane_b32 s44, v210, 34
	s_nop 0
	s_movk_i32 s2, 0x6000
	s_nop 0
	s_movk_i32 s2, 0x7000
	s_nop 0
	s_mov_b32 s2, 0x8000
	s_nop 0
	s_mov_b32 s2, 0x9000
	s_nop 0
	s_mov_b32 s2, 0xa000
	s_nop 0
	s_mov_b32 s2, 0xc000
	s_nop 0
	s_nop 0
	s_nop 0
	s_mov_b32 s2, 0xd000
	s_nop 0
	s_mov_b32 s2, 0xe000
	s_nop 0
	s_mov_b32 s2, 0xf000
	s_nop 0
	s_nop 0
	s_nop 0
	s_nop 0
	s_nop 0
	s_nop 0
	s_nop 0
	s_nop 0
	s_nop 0
	s_nop 0
	s_nop 0
	s_nop 0
	s_nop 0
	v_add_u32_e32 v46, s7, v48
	v_ashrrev_i32_e32 v47, 31, v46
	v_lshlrev_b64 v[46:47], 2, v[46:47]
	v_readlane_b32 s48, v210, 38
	v_readlane_b32 s49, v210, 39
	v_readlane_b32 s50, v210, 40
	v_readlane_b32 s51, v210, 41
	v_lshl_add_u64 v[50:51], s[48:49], 0, v[46:47]
	global_load_dword v82, v[50:51], off
	v_lshl_add_u64 v[46:47], s[50:51], 0, v[46:47]
	global_load_dword v83, v[46:47], off
	v_readlane_b32 s45, v210, 35
	v_readlane_b32 s46, v210, 36
	v_readlane_b32 s47, v210, 37
	v_readlane_b32 s52, v210, 42
	v_readlane_b32 s53, v210, 43
	v_readlane_b32 s54, v210, 44
	v_readlane_b32 s55, v210, 45
	v_readlane_b32 s56, v210, 46
	v_readlane_b32 s57, v210, 47
	v_readlane_b32 s58, v210, 48
	v_readlane_b32 s59, v210, 49
	s_ashr_i32 s35, s34, 31
	v_readlane_b32 s44, v210, 50
	s_lshl_b64 s[2:3], s[34:35], 11
	s_lshl_b64 s[36:37], s[34:35], 4
	s_lshl_b64 s[38:39], s[34:35], 10
	v_readlane_b32 s46, v210, 52
	v_readlane_b32 s47, v210, 53
	s_add_u32 s2, s46, s2
	s_addc_u32 s3, s47, s3
	s_mul_i32 s9, s34, 0xf00
	v_ashrrev_i32_e32 v52, 6, v48
	v_lshl_add_u64 v[48:49], v[48:49], 1, s[2:3]
	v_readlane_b32 s2, v208, 22
	s_mul_hi_i32 s5, s34, 0xf00
	s_add_u32 s2, s2, s9
	s_addc_u32 s3, s69, s5
	v_lshl_add_u64 v[50:51], s[2:3], 0, v[54:55]
	s_add_u32 s2, s24, s36
	v_ashrrev_i32_e32 v53, 31, v52
	v_readlane_b32 s45, v210, 51
	s_addc_u32 s3, s25, s37
	v_lshl_add_u64 v[56:57], s[38:39], 0, v[54:55]
	s_mov_b32 s4, 0
	v_lshl_add_u64 v[52:53], v[52:53], 2, s[2:3]
	v_lshl_add_u64 v[54:55], s[26:27], 0, v[56:57]
	v_lshl_add_u64 v[56:57], s[44:45], 0, v[56:57]
	s_mov_b64 s[2:3], 0
	s_waitcnt lgkmcnt(0)
	s_barrier
	v_readlane_b32 s48, v210, 54
	v_readlane_b32 s49, v210, 55
	v_readlane_b32 s50, v210, 56
	v_readlane_b32 s51, v210, 57
	v_readlane_b32 s52, v210, 58
	v_readlane_b32 s53, v210, 59
	v_readlane_b32 s54, v210, 60
	v_readlane_b32 s55, v210, 61
	v_readlane_b32 s56, v210, 62
	v_readlane_b32 s57, v210, 63
	v_readlane_b32 s58, v209, 0
	v_readlane_b32 s59, v209, 1
	s_mov_b64 s[36:37], 0xf00
	v_mov_b32_e32 v94, 0
	ds_read_b128 v[136:139], v94 offset:0
	ds_read_b128 v[140:143], v94 offset:16
	ds_read_b128 v[144:147], v94 offset:32
	ds_read_b128 v[148:151], v94 offset:48
	ds_read_b128 v[152:155], v94 offset:64
	ds_read_b128 v[156:159], v94 offset:80
	ds_read_b128 v[160:163], v94 offset:96
	ds_read_b128 v[164:167], v94 offset:112
	ds_read_b128 v[184:187], v94 offset:128
	ds_read_b128 v[188:191], v94 offset:144
	ds_read_b128 v[192:195], v94 offset:160
	ds_read_b128 v[196:199], v94 offset:176
	ds_read_b128 v[200:203], v94 offset:192
	ds_read_b128 v[212:215], v94 offset:208
	ds_read_b128 v[216:219], v94 offset:224
	ds_read_b128 v[220:223], v94 offset:240
	v_lshl_add_u64 v[94:95], v[54:55], 0, s[2:3]
	global_load_dword v84, v[94:95], off
	v_lshl_add_u64 v[94:95], v[56:57], 0, s[2:3]
	global_load_dword v85, v[94:95], off
	global_load_dword v86, v[52:53], off
	global_load_dword v87, v[50:51], off
	s_add_u32 s2, s2, 0x400
	s_addc_u32 s3, s3, 0
	v_lshl_add_u64 v[52:53], v[52:53], 0, 16
	v_lshl_add_u64 v[50:51], v[50:51], 0, s[36:37]
.LBB0_1129:
	v_mov_b32_e32 v94, s4
	s_waitcnt vmcnt(0)
	v_add_f32_e32 v88, v84, v85
	v_mul_f32_e32 v86, v86, v87
	v_mov_b32_e32 v89, v88
	s_waitcnt lgkmcnt(15)
	v_pk_mul_f32 v[92:93], v[136:137], v[2:3]
	v_pk_fma_f32 v[92:93], v[138:139], v[4:5], v[92:93]
	ds_read_b128 v[136:139], v94 offset:256
	v_add_f32_dpp v89, v89, v89 quad_perm:[1,0,3,2] row_mask:0xf bank_mask:0xf bound_ctrl:1
	s_waitcnt lgkmcnt(15)
	v_pk_fma_f32 v[92:93], v[140:141], v[6:7], v[92:93]
	v_pk_fma_f32 v[92:93], v[142:143], v[8:9], v[92:93]
	ds_read_b128 v[140:143], v94 offset:272
	v_add_f32_dpp v89, v89, v89 quad_perm:[2,3,0,1] row_mask:0xf bank_mask:0xf bound_ctrl:1
	s_waitcnt lgkmcnt(15)
	v_pk_fma_f32 v[92:93], v[144:145], v[10:11], v[92:93]
	v_pk_fma_f32 v[92:93], v[146:147], v[12:13], v[92:93]
	ds_read_b128 v[144:147], v94 offset:288
	v_add_f32_dpp v89, v89, v89 row_half_mirror row_mask:0xf bank_mask:0xf bound_ctrl:1
	s_waitcnt lgkmcnt(15)
	v_pk_fma_f32 v[92:93], v[148:149], v[14:15], v[92:93]
	v_pk_fma_f32 v[92:93], v[150:151], v[16:17], v[92:93]
	ds_read_b128 v[148:151], v94 offset:304
	v_add_f32_dpp v89, v89, v89 row_mirror row_mask:0xf bank_mask:0xf bound_ctrl:1
	s_waitcnt lgkmcnt(15)
	v_pk_fma_f32 v[92:93], v[152:153], v[18:19], v[92:93]
	v_pk_fma_f32 v[92:93], v[154:155], v[20:21], v[92:93]
	ds_read_b128 v[152:155], v94 offset:320
	v_add_f32_dpp v89, v89, v89 row_bcast:15 row_mask:0xa bank_mask:0xf
	s_waitcnt lgkmcnt(15)
	v_pk_fma_f32 v[92:93], v[156:157], v[22:23], v[92:93]
	v_pk_fma_f32 v[92:93], v[158:159], v[24:25], v[92:93]
	ds_read_b128 v[156:159], v94 offset:336
	v_add_f32_dpp v89, v89, v89 row_bcast:31 row_mask:0xc bank_mask:0xf
	s_waitcnt lgkmcnt(15)
	v_pk_fma_f32 v[92:93], v[160:161], v[26:27], v[92:93]
	v_pk_fma_f32 v[92:93], v[162:163], v[28:29], v[92:93]
	ds_read_b128 v[160:163], v94 offset:352
	v_readlane_b32 s5, v89, 63
	s_waitcnt lgkmcnt(15)
	v_pk_fma_f32 v[92:93], v[164:165], v[30:31], v[92:93]
	v_pk_fma_f32 v[92:93], v[166:167], v[32:33], v[92:93]
	ds_read_b128 v[164:167], v94 offset:368
	v_mov_b32_e32 v89, s5
	v_fmac_f32_e32 v88, 0xbc800000, v89
	s_waitcnt lgkmcnt(15)
	v_pk_fma_f32 v[92:93], v[184:185], v[34:35], v[92:93]
	v_pk_fma_f32 v[92:93], v[186:187], v[36:37], v[92:93]
	ds_read_b128 v[184:187], v94 offset:384
	v_mul_f32_e32 v90, v88, v88
	s_waitcnt lgkmcnt(15)
	v_pk_fma_f32 v[92:93], v[188:189], v[38:39], v[92:93]
	v_pk_fma_f32 v[92:93], v[190:191], v[40:41], v[92:93]
	ds_read_b128 v[188:191], v94 offset:400
	v_add_f32_dpp v90, v90, v90 quad_perm:[1,0,3,2] row_mask:0xf bank_mask:0xf bound_ctrl:1
	s_waitcnt lgkmcnt(15)
	v_pk_fma_f32 v[92:93], v[192:193], v[58:59], v[92:93]
	v_pk_fma_f32 v[92:93], v[194:195], v[60:61], v[92:93]
	ds_read_b128 v[192:195], v94 offset:416
	v_add_f32_dpp v90, v90, v90 quad_perm:[2,3,0,1] row_mask:0xf bank_mask:0xf bound_ctrl:1
	s_waitcnt lgkmcnt(15)
	v_pk_fma_f32 v[92:93], v[196:197], v[62:63], v[92:93]
	v_pk_fma_f32 v[92:93], v[198:199], v[64:65], v[92:93]
	ds_read_b128 v[196:199], v94 offset:432
	v_add_f32_dpp v90, v90, v90 row_half_mirror row_mask:0xf bank_mask:0xf bound_ctrl:1
	s_waitcnt lgkmcnt(15)
	v_pk_fma_f32 v[92:93], v[200:201], v[66:67], v[92:93]
	v_pk_fma_f32 v[92:93], v[202:203], v[68:69], v[92:93]
	ds_read_b128 v[200:203], v94 offset:448
	v_add_f32_dpp v90, v90, v90 row_mirror row_mask:0xf bank_mask:0xf bound_ctrl:1
	s_waitcnt lgkmcnt(15)
	v_pk_fma_f32 v[92:93], v[212:213], v[70:71], v[92:93]
	v_pk_fma_f32 v[92:93], v[214:215], v[72:73], v[92:93]
	ds_read_b128 v[212:215], v94 offset:464
	v_add_f32_dpp v90, v90, v90 row_bcast:15 row_mask:0xa bank_mask:0xf
	s_waitcnt lgkmcnt(15)
	v_pk_fma_f32 v[92:93], v[216:217], v[74:75], v[92:93]
	v_pk_fma_f32 v[92:93], v[218:219], v[76:77], v[92:93]
	ds_read_b128 v[216:219], v94 offset:480
	v_add_f32_dpp v90, v90, v90 row_bcast:31 row_mask:0xc bank_mask:0xf
	s_waitcnt lgkmcnt(15)
	v_pk_fma_f32 v[92:93], v[220:221], v[78:79], v[92:93]
	v_pk_fma_f32 v[92:93], v[222:223], v[80:81], v[92:93]
	ds_read_b128 v[220:223], v94 offset:496
	s_nop 1
	v_readlane_b32 s5, v90, 63
	v_add_f32_e32 v94, v92, v93
	v_mov_b32_e32 v95, s5
	v_fmamk_f32 v95, v95, 0x3c800000, v176
	v_rsq_f32_e32 v95, v95
	v_mul_f32_e32 v88, v88, v82
	s_addk_i32 s4, 0x100
	v_fma_f32 v88, v88, v95, v83
	v_add_f32_e32 v88, v88, v86
	v_mul_f32_e32 v88, v88, v94
	v_cvt_pk_bf16_f32 v88, v88, s0
	s_mov_b64 s[38:39], 0x800
	global_store_short v[48:49], v88, off
	v_lshl_add_u64 v[48:49], v[48:49], 0, s[38:39]
	s_cmpk_eq_i32 s4, 0x2200
	s_cbranch_scc1 .Lro_done
	v_lshl_add_u64 v[94:95], v[54:55], 0, s[2:3]
	global_load_dword v84, v[94:95], off
	v_lshl_add_u64 v[94:95], v[56:57], 0, s[2:3]
	global_load_dword v85, v[94:95], off
	global_load_dword v86, v[52:53], off
	global_load_dword v87, v[50:51], off
	s_add_u32 s2, s2, 0x400
	s_addc_u32 s3, s3, 0
	v_lshl_add_u64 v[52:53], v[52:53], 0, 16
	v_lshl_add_u64 v[50:51], v[50:51], 0, s[36:37]
	s_branch .LBB0_1129
.Lro_done:
	s_waitcnt lgkmcnt(0)
	s_mov_b32 s2, 0x8800
	s_mov_b32 s3, 0
	v_readlane_b32 s2, v208, 21
	s_add_i32 s8, s8, s66
	s_add_i32 s34, s34, s2
	s_cmp_lt_i32 s8, s6
	s_barrier
	s_cbranch_scc1 .LBB0_1125
	v_readlane_b32 s42, v208, 51
	v_readlane_b32 s54, v209, 14
	v_readlane_b32 s43, v208, 52
	v_readlane_b32 s55, v209, 15
	s_mov_b32 s56, 0x10000
	s_mov_b32 s57, 0x20000
	s_mov_b32 s58, 0x30000
	s_movk_i32 s59, 0x70
	s_movk_i32 s53, 0x2000
	s_mov_b32 s52, 0xb000
